# mixer-phase queues: the 128 workgroups of ranks 16..31 (bx >= 128) start on the decode list instead of 16
# speedup vs baseline: 1.0083x; 1.0083x over previous
; DEV int lane_id() { int l; asm volatile("v_mbcnt_lo_u32_b32 %0, -1, 0\n\tv_mbcnt_hi_u32_b32 %0, -1, %0" : "=v"(l)); return l; }
; #define LAS __attribute__((address_space(3)))
; __global__ void __launch_bounds__(512, 2) mk_fwd(MKArgs args) {
;     ...
;         if (IN(pb + 2)) { LAYER_PTRS
;             { volatile LAS unsigned* LQ = (volatile LAS unsigned*)(ldsl + LDSCTL_OFF + 512);
;               unsigned* qd = (unsigned*)(ws + WS_CTL) + CW_Q3 + 128 * l; unsigned* qa = qd + 64;
;               const bool dclass = (bx >> 3) == 19 || (bx >> 3) == 27;
;               constexpr unsigned ND = SB * NSPLIT, NA = NB * MH * 8 + M / 256;
;               for (;;) {
;                   if (wave_s == 0 && lane_id() == 0) { unsigned kind = 2u, idx = 0u;
;                       if (dclass) { idx = __hip_atomic_fetch_add(qd, 1u, __ATOMIC_RELAXED, __HIP_MEMORY_SCOPE_AGENT); if (idx < ND) kind = 0u; else { idx = __hip_atomic_fetch_add(qa, 1u, __ATOMIC_RELAXED, __HIP_MEMORY_SCOPE_AGENT); if (idx < NA) kind = 1u; } }
;                       else { idx = __hip_atomic_fetch_add(qa, 1u, __ATOMIC_RELAXED, __HIP_MEMORY_SCOPE_AGENT); if (idx < NA) kind = 1u; else { idx = __hip_atomic_fetch_add(qd, 1u, __ATOMIC_RELAXED, __HIP_MEMORY_SCOPE_AGENT); if (idx < ND) kind = 0u; } }
;                       LQ[0] = kind; LQ[1] = idx; }
.LBB0_1240:
	s_waitcnt lgkmcnt(0)
	v_readlane_b32 s10, v255, 0
	v_readlane_b32 s14, v254, 1
	s_lshl_b32 s4, s10, 11
	v_readlane_b32 s15, v254, 2
	v_readlane_b32 s11, v255, 1
	s_barrier
	v_writelane_b32 v255, s4, 31
	v_readlane_b32 s4, v254, 9
	s_lshl_b32 s6, s10, 12
	s_load_dwordx2 s[22:23], s[14:15], 0x120
	v_readlane_b32 s5, v254, 10
	v_writelane_b32 v255, s6, 33
	s_load_dword s4, s[4:5], 0x0
	v_readlane_b32 s5, v254, 0
	v_writelane_b32 v255, s7, 34
	s_mov_b32 s6, s57
	s_waitcnt lgkmcnt(0)
	s_lshl_b64 s[0:1], s[10:11], 14
	s_lshl_b64 s[2:3], s[10:11], 20
	s_add_i32 s50, s6, 0
	v_readlane_b32 s4, v254, 52
	s_add_u32 s4, s22, s4
	s_addc_u32 s6, s23, 0
	s_add_i32 s51, s50, 0x20200
	s_lshl_b64 s[8:9], s[38:39], 2
	s_add_u32 s7, s22, s8
	v_writelane_b32 v255, s8, 40
	s_mul_hi_u32 s26, s10, 0x1400
	s_mul_i32 s27, s10, 0x1400
	v_writelane_b32 v255, s9, 41
	s_addc_u32 s8, s23, s9
	s_add_u32 s12, s7, 0xa6040
	s_addc_u32 s13, s8, 0
	v_writelane_b32 v255, s12, 26
	s_nop 1
	v_writelane_b32 v255, s13, 27
	s_add_u32 s12, s7, 0xa6140
	s_addc_u32 s13, s8, 0
	s_and_b32 s5, s5, 0x80
	s_cmpk_lg_i32 s5, 0x80
	s_cselect_b64 s[8:9], -1, 0
	s_add_i32 s52, s50, 0x20204
	s_add_i32 s53, s50, 0x17a00
	s_add_i32 s62, s50, 0x19e00
	s_add_u32 s63, s22, 0x1a798300
	s_addc_u32 s72, s23, 0
	s_add_i32 s73, s50, 0x15000
	s_add_i32 s78, s50, 0x1a000
	s_add_i32 s5, s50, 0x18e00
	s_add_u32 s2, s22, s2
	s_addc_u32 s3, s23, s3
	s_add_u32 s88, s2, 0x1a7d5300
	s_addc_u32 s89, s3, 0
	s_add_u32 s0, s22, s0
	s_addc_u32 s1, s23, s1
	s_add_u32 s40, s0, 0x1abd5300
	s_addc_u32 s41, s1, 0
	v_writelane_b32 v254, s5, 50
	s_add_u32 s0, s22, 0x9c400
	v_writelane_b32 v254, s0, 62
	s_addc_u32 s0, s23, 0
	v_writelane_b32 v254, s0, 60
	s_add_u32 s0, s22, 0x1a7c0300
	s_addc_u32 s37, s23, 0
	v_writelane_b32 v254, s0, 54
	s_add_u32 s0, s22, 0x1a7c5500
	v_writelane_b32 v254, s0, 58
	v_writelane_b32 v255, s12, 29
	v_readlane_b32 s0, v254, 47
	v_readlane_b32 s1, v254, 48
	v_writelane_b32 v255, s13, 30
	v_writelane_b32 v255, s8, 6
	s_addc_u32 s36, s23, 0
	s_lshl_b64 s[2:3], s[0:1], 2
	v_writelane_b32 v255, s9, 7
	s_add_u32 s0, s22, s2
	v_writelane_b32 v255, s2, 42
	s_addc_u32 s1, s23, s3
	s_add_u32 s0, s0, 0xce800
	v_writelane_b32 v255, s3, 43
	s_addc_u32 s1, s1, 0
	v_writelane_b32 v255, s0, 44
	s_nop 1
	v_writelane_b32 v255, s1, 45
	s_add_u32 s0, s22, 0xee58100
	v_writelane_b32 v255, s0, 10
	s_addc_u32 s0, s23, 0
	v_writelane_b32 v255, s0, 12
	s_add_u32 s0, s22, 0xfe58100
	v_writelane_b32 v254, s0, 49
	s_addc_u32 s0, s23, 0
	v_writelane_b32 v255, s0, 8
	s_add_u32 s0, s22, 0x10658100
	v_writelane_b32 v255, s0, 32
	s_addc_u32 s0, s23, 0
	v_writelane_b32 v255, s0, 18
	s_add_u32 s0, s22, 0x11658100
	v_writelane_b32 v255, s0, 20
	s_addc_u32 s0, s23, 0
	v_writelane_b32 v255, s0, 22
	s_add_u32 s0, s22, 0x11758100
	v_writelane_b32 v255, s0, 24
	s_addc_u32 s0, s23, 0
	v_writelane_b32 v255, s0, 28
	s_add_u32 s0, s22, 0xbc800
	v_writelane_b32 v255, s0, 14
	s_addc_u32 s0, s23, 0
	s_add_u32 s60, s22, 0x12758100
	s_addc_u32 s61, s23, 0
	s_add_u32 s64, s4, 0x4e0000
	s_addc_u32 s65, s6, 0
	s_add_u32 s42, s22, 0x12f58100
	s_addc_u32 s43, s23, 0
	s_add_i32 s38, s50, 0x10000
	v_writelane_b32 v255, s0, 46
	s_add_u32 s0, s4, 0x4f0000
	s_addc_u32 s1, s6, 0
	s_add_i32 s39, s50, 0x14000
	s_add_u32 s20, s4, 0x4e0080
	s_addc_u32 s21, s6, 0
	s_add_i32 s24, s50, 0x18000
	s_add_u32 s70, s4, 0x4f0080
	s_addc_u32 s71, s6, 0
	s_add_i32 s25, s50, 0x1c000
	s_add_u32 s80, s4, 0x4e0100
	s_addc_u32 s81, s6, 0
	s_add_u32 s2, s4, 0x4f0100
	s_addc_u32 s3, s6, 0
	s_add_u32 s58, s4, 0x4e0180
	s_addc_u32 s59, s6, 0
	s_add_u32 s54, s4, 0x4f0180
	s_addc_u32 s55, s6, 0
	s_branch .LBB0_1246
